# grid barrier release flattened: XCD members poll the top-level generation word directly instead of the per-XCD relay word
# speedup vs baseline: 1.0111x; 1.0010x over previous
; __device__ __forceinline__ unsigned xb_ld(unsigned* p)              { return __hip_atomic_load(p, __ATOMIC_RELAXED, __HIP_MEMORY_SCOPE_AGENT); }
; __device__ __forceinline__ unsigned xb_add(unsigned* p, unsigned v) { return __hip_atomic_fetch_add(p, v, __ATOMIC_RELAXED, __HIP_MEMORY_SCOPE_AGENT); }
; #define XB_SPIN(cond, bar) do { unsigned _sp = 0; while (cond) { __builtin_amdgcn_s_sleep(1); \
;     if ((++_sp & 255u) == 0u) { if (xb_ld(&(bar)[XB_TMO])) break; if (_sp > XB_SPIN_CAP) { atomicAdd(&(bar)[XB_TMO], 1u); break; } } } } while (0)
; __device__ __forceinline__ void xcd_barrier(const XcdBarrier& b, bool leader) {
;     ...
;         if (nloc == 0u) { xcd_barrier_complete(bar, b.x, nloc, nx); b.st[0] = nloc; b.st[1] = nx; }
;         const unsigned old = xb_add(&bar[XB_XSUB(b.x)], 1u);
;         const unsigned gen = old / nloc;
;         if (old + 1u == (gen + 1u) * nloc) {
;             __builtin_amdgcn_fence(__ATOMIC_RELEASE, "agent");
;             asm volatile("s_waitcnt vmcnt(0)" ::: "memory");
;             const unsigned og = xb_add(&bar[XB_TOP], 1u);
;             const unsigned tg = og / nx;
;             if (og + 1u == (tg + 1u) * nx) xb_add(&bar[XB_TOPGEN], 1u);
;             else XB_SPIN(xb_ld(&bar[XB_TOPGEN]) == tg, bar);
;             __builtin_amdgcn_fence(__ATOMIC_ACQUIRE, "agent");
;             xb_add(&bar[XB_XGEN(b.x)], 1u);
;             asm volatile("s_waitcnt vmcnt(0)" ::: "memory");
;         } else {
;             XB_SPIN(xb_ld(&bar[XB_XGEN(b.x)]) == gen, bar);
.LBB0_144:
	s_or_b64 exec, exec, s[10:11]
	v_cvt_f32_u32_e32 v4, v2
	s_waitcnt vmcnt(0)
	v_readfirstlane_b32 s8, v3
	v_sub_u32_e32 v3, 0, v2
	v_rcp_iflag_f32_e32 v4, v4
	v_add_u32_e32 v5, s8, v1
	v_mul_f32_e32 v4, 0x4f7ffffe, v4
	v_cvt_u32_f32_e32 v4, v4
	v_mul_lo_u32 v1, v3, v4
	v_mul_hi_u32 v1, v4, v1
	v_add_u32_e32 v1, v4, v1
	v_mul_hi_u32 v1, v5, v1
	v_mul_lo_u32 v3, v1, v2
	v_sub_u32_e32 v3, v5, v3
	v_add_u32_e32 v4, 1, v1
	v_cmp_ge_u32_e32 vcc, v3, v2
	s_nop 1
	v_cndmask_b32_e32 v1, v1, v4, vcc
	v_sub_u32_e32 v4, v3, v2
	v_cndmask_b32_e32 v3, v3, v4, vcc
	v_add_u32_e32 v4, 1, v1
	v_cmp_ge_u32_e32 vcc, v3, v2
	v_add_u32_e32 v3, 1, v5
	s_nop 0
	v_cndmask_b32_e32 v1, v1, v4, vcc
	v_mul_lo_u32 v4, v2, v1
	v_add_u32_e32 v2, v4, v2
	v_cmp_ne_u32_e32 vcc, v3, v2
	s_and_saveexec_b64 s[8:9], vcc
	s_xor_b64 s[8:9], exec, s[8:9]
	s_cbranch_execz .LBB0_158
	buffer_inv sc1
	s_waitcnt lgkmcnt(0)
	v_mov_b32_e32 v0, 0x3000
	global_load_dword v0, v0, s[76:77] offset:1280 sc1
	s_add_u32 s14, s76, 0x3500
	s_addc_u32 s15, s77, 0
	s_waitcnt vmcnt(0)
	v_cmp_eq_u32_e32 vcc, v0, v1
	s_and_saveexec_b64 s[10:11], vcc
	s_cbranch_execz .LBB0_157
	s_mov_b32 s13, 1
	s_mov_b64 s[16:17], 0
	v_mov_b32_e32 v0, 0
	s_branch .LBB0_148

; __device__ __forceinline__ unsigned xb_ld(unsigned* p)              { return __hip_atomic_load(p, __ATOMIC_RELAXED, __HIP_MEMORY_SCOPE_AGENT); }
; __device__ __forceinline__ unsigned xb_add(unsigned* p, unsigned v) { return __hip_atomic_fetch_add(p, v, __ATOMIC_RELAXED, __HIP_MEMORY_SCOPE_AGENT); }
; #define XB_SPIN(cond, bar) do { unsigned _sp = 0; while (cond) { __builtin_amdgcn_s_sleep(1); \
;     if ((++_sp & 255u) == 0u) { if (xb_ld(&(bar)[XB_TMO])) break; if (_sp > XB_SPIN_CAP) { atomicAdd(&(bar)[XB_TMO], 1u); break; } } } } while (0)
; __device__ __forceinline__ void xcd_barrier(const XcdBarrier& b, bool leader) {
;     ...
;         if (nloc == 0u) { xcd_barrier_complete(bar, b.x, nloc, nx); b.st[0] = nloc; b.st[1] = nx; }
;         const unsigned old = xb_add(&bar[XB_XSUB(b.x)], 1u);
;         const unsigned gen = old / nloc;
;         if (old + 1u == (gen + 1u) * nloc) {
;             __builtin_amdgcn_fence(__ATOMIC_RELEASE, "agent");
;             asm volatile("s_waitcnt vmcnt(0)" ::: "memory");
;             const unsigned og = xb_add(&bar[XB_TOP], 1u);
;             const unsigned tg = og / nx;
;             if (og + 1u == (tg + 1u) * nx) xb_add(&bar[XB_TOPGEN], 1u);
;             else XB_SPIN(xb_ld(&bar[XB_TOPGEN]) == tg, bar);
;             __builtin_amdgcn_fence(__ATOMIC_ACQUIRE, "agent");
;             xb_add(&bar[XB_XGEN(b.x)], 1u);
;             asm volatile("s_waitcnt vmcnt(0)" ::: "memory");
;         } else {
;             XB_SPIN(xb_ld(&bar[XB_XGEN(b.x)]) == gen, bar);
.LBB0_363:
	s_or_b64 exec, exec, s[10:11]
	v_cvt_f32_u32_e32 v4, v2
	s_waitcnt vmcnt(0)
	v_readfirstlane_b32 s8, v3
	v_sub_u32_e32 v3, 0, v2
	v_rcp_iflag_f32_e32 v4, v4
	v_add_u32_e32 v5, s8, v1
	v_mul_f32_e32 v4, 0x4f7ffffe, v4
	v_cvt_u32_f32_e32 v4, v4
	v_mul_lo_u32 v1, v3, v4
	v_mul_hi_u32 v1, v4, v1
	v_add_u32_e32 v1, v4, v1
	v_mul_hi_u32 v1, v5, v1
	v_mul_lo_u32 v3, v1, v2
	v_sub_u32_e32 v3, v5, v3
	v_add_u32_e32 v4, 1, v1
	v_cmp_ge_u32_e32 vcc, v3, v2
	s_nop 1
	v_cndmask_b32_e32 v1, v1, v4, vcc
	v_sub_u32_e32 v4, v3, v2
	v_cndmask_b32_e32 v3, v3, v4, vcc
	v_add_u32_e32 v4, 1, v1
	v_cmp_ge_u32_e32 vcc, v3, v2
	v_add_u32_e32 v3, 1, v5
	s_nop 0
	v_cndmask_b32_e32 v1, v1, v4, vcc
	v_mul_lo_u32 v4, v2, v1
	v_add_u32_e32 v2, v4, v2
	v_cmp_ne_u32_e32 vcc, v3, v2
	s_and_saveexec_b64 s[8:9], vcc
	s_xor_b64 s[8:9], exec, s[8:9]
	s_cbranch_execz .LBB0_377
	buffer_inv sc1
	s_waitcnt lgkmcnt(0)
	v_mov_b32_e32 v0, 0x3000
	global_load_dword v0, v0, s[76:77] offset:1280 sc1
	s_add_u32 s12, s76, 0x3500
	s_addc_u32 s13, s77, 0
	s_waitcnt vmcnt(0)
	v_cmp_eq_u32_e32 vcc, v0, v1
	s_and_saveexec_b64 s[10:11], vcc
	s_cbranch_execz .LBB0_376
	s_mov_b32 s24, 1
	s_mov_b64 s[14:15], 0
	v_mov_b32_e32 v0, 0
	s_branch .LBB0_367

; __device__ __forceinline__ unsigned xb_ld(unsigned* p)              { return __hip_atomic_load(p, __ATOMIC_RELAXED, __HIP_MEMORY_SCOPE_AGENT); }
; __device__ __forceinline__ unsigned xb_add(unsigned* p, unsigned v) { return __hip_atomic_fetch_add(p, v, __ATOMIC_RELAXED, __HIP_MEMORY_SCOPE_AGENT); }
; #define XB_SPIN(cond, bar) do { unsigned _sp = 0; while (cond) { __builtin_amdgcn_s_sleep(1); \
;     if ((++_sp & 255u) == 0u) { if (xb_ld(&(bar)[XB_TMO])) break; if (_sp > XB_SPIN_CAP) { atomicAdd(&(bar)[XB_TMO], 1u); break; } } } } while (0)
; __device__ __forceinline__ void xcd_barrier(const XcdBarrier& b, bool leader) {
;     ...
;         if (nloc == 0u) { xcd_barrier_complete(bar, b.x, nloc, nx); b.st[0] = nloc; b.st[1] = nx; }
;         const unsigned old = xb_add(&bar[XB_XSUB(b.x)], 1u);
;         const unsigned gen = old / nloc;
;         if (old + 1u == (gen + 1u) * nloc) {
;             __builtin_amdgcn_fence(__ATOMIC_RELEASE, "agent");
;             asm volatile("s_waitcnt vmcnt(0)" ::: "memory");
;             const unsigned og = xb_add(&bar[XB_TOP], 1u);
;             const unsigned tg = og / nx;
;             if (og + 1u == (tg + 1u) * nx) xb_add(&bar[XB_TOPGEN], 1u);
;             else XB_SPIN(xb_ld(&bar[XB_TOPGEN]) == tg, bar);
;             __builtin_amdgcn_fence(__ATOMIC_ACQUIRE, "agent");
;             xb_add(&bar[XB_XGEN(b.x)], 1u);
;             asm volatile("s_waitcnt vmcnt(0)" ::: "memory");
;         } else {
;             XB_SPIN(xb_ld(&bar[XB_XGEN(b.x)]) == gen, bar);
.LBB0_1428:
	s_or_b64 exec, exec, s[10:11]
	v_cvt_f32_u32_e32 v4, v2
	s_waitcnt vmcnt(0)
	v_readfirstlane_b32 s3, v3
	v_sub_u32_e32 v3, 0, v2
	v_rcp_iflag_f32_e32 v4, v4
	v_add_u32_e32 v5, s3, v1
	v_mul_f32_e32 v4, 0x4f7ffffe, v4
	v_cvt_u32_f32_e32 v4, v4
	v_mul_lo_u32 v1, v3, v4
	v_mul_hi_u32 v1, v4, v1
	v_add_u32_e32 v1, v4, v1
	v_mul_hi_u32 v1, v5, v1
	v_mul_lo_u32 v3, v1, v2
	v_sub_u32_e32 v3, v5, v3
	v_add_u32_e32 v4, 1, v1
	v_cmp_ge_u32_e32 vcc, v3, v2
	s_nop 1
	v_cndmask_b32_e32 v1, v1, v4, vcc
	v_sub_u32_e32 v4, v3, v2
	v_cndmask_b32_e32 v3, v3, v4, vcc
	v_add_u32_e32 v4, 1, v1
	v_cmp_ge_u32_e32 vcc, v3, v2
	v_add_u32_e32 v3, 1, v5
	s_nop 0
	v_cndmask_b32_e32 v1, v1, v4, vcc
	v_mul_lo_u32 v4, v2, v1
	v_add_u32_e32 v2, v4, v2
	v_cmp_ne_u32_e32 vcc, v3, v2
	s_and_saveexec_b64 s[8:9], vcc
	s_xor_b64 s[8:9], exec, s[8:9]
	s_cbranch_execz .LBB0_1446
	buffer_inv sc1
	s_waitcnt lgkmcnt(0)
	v_mov_b32_e32 v0, 0x3000
	global_load_dword v0, v0, s[76:77] offset:1280 sc1
	s_add_u32 s12, s76, 0x3500
	s_addc_u32 s13, s77, 0
	s_waitcnt vmcnt(0)
	v_cmp_eq_u32_e32 vcc, v0, v1
	s_and_saveexec_b64 s[10:11], vcc
	s_cbranch_execz .LBB0_1445
	s_mov_b32 s3, 1
	s_mov_b64 s[14:15], 0
	v_mov_b32_e32 v0, 0
	s_branch .LBB0_1432

; __device__ __forceinline__ unsigned xb_ld(unsigned* p)              { return __hip_atomic_load(p, __ATOMIC_RELAXED, __HIP_MEMORY_SCOPE_AGENT); }
; __device__ __forceinline__ unsigned xb_add(unsigned* p, unsigned v) { return __hip_atomic_fetch_add(p, v, __ATOMIC_RELAXED, __HIP_MEMORY_SCOPE_AGENT); }
; #define XB_SPIN(cond, bar) do { unsigned _sp = 0; while (cond) { __builtin_amdgcn_s_sleep(1); \
;     if ((++_sp & 255u) == 0u) { if (xb_ld(&(bar)[XB_TMO])) break; if (_sp > XB_SPIN_CAP) { atomicAdd(&(bar)[XB_TMO], 1u); break; } } } } while (0)
; __device__ __forceinline__ void xcd_barrier(const XcdBarrier& b, bool leader) {
;     ...
;         if (nloc == 0u) { xcd_barrier_complete(bar, b.x, nloc, nx); b.st[0] = nloc; b.st[1] = nx; }
;         const unsigned old = xb_add(&bar[XB_XSUB(b.x)], 1u);
;         const unsigned gen = old / nloc;
;         if (old + 1u == (gen + 1u) * nloc) {
;             __builtin_amdgcn_fence(__ATOMIC_RELEASE, "agent");
;             asm volatile("s_waitcnt vmcnt(0)" ::: "memory");
;             const unsigned og = xb_add(&bar[XB_TOP], 1u);
;             const unsigned tg = og / nx;
;             if (og + 1u == (tg + 1u) * nx) xb_add(&bar[XB_TOPGEN], 1u);
;             else XB_SPIN(xb_ld(&bar[XB_TOPGEN]) == tg, bar);
;             __builtin_amdgcn_fence(__ATOMIC_ACQUIRE, "agent");
;             xb_add(&bar[XB_XGEN(b.x)], 1u);
;             asm volatile("s_waitcnt vmcnt(0)" ::: "memory");
;         } else {
;             XB_SPIN(xb_ld(&bar[XB_XGEN(b.x)]) == gen, bar);
.LBB0_2150:
	s_or_b64 exec, exec, s[12:13]
	v_cvt_f32_u32_e32 v4, v2
	s_waitcnt vmcnt(0)
	v_readfirstlane_b32 s3, v3
	v_sub_u32_e32 v3, 0, v2
	v_rcp_iflag_f32_e32 v4, v4
	v_add_u32_e32 v5, s3, v1
	v_mul_f32_e32 v4, 0x4f7ffffe, v4
	v_cvt_u32_f32_e32 v4, v4
	v_mul_lo_u32 v1, v3, v4
	v_mul_hi_u32 v1, v4, v1
	v_add_u32_e32 v1, v4, v1
	v_mul_hi_u32 v1, v5, v1
	v_mul_lo_u32 v3, v1, v2
	v_sub_u32_e32 v3, v5, v3
	v_add_u32_e32 v4, 1, v1
	v_cmp_ge_u32_e32 vcc, v3, v2
	s_nop 1
	v_cndmask_b32_e32 v1, v1, v4, vcc
	v_sub_u32_e32 v4, v3, v2
	v_cndmask_b32_e32 v3, v3, v4, vcc
	v_add_u32_e32 v4, 1, v1
	v_cmp_ge_u32_e32 vcc, v3, v2
	v_add_u32_e32 v3, 1, v5
	s_nop 0
	v_cndmask_b32_e32 v1, v1, v4, vcc
	v_mul_lo_u32 v4, v2, v1
	v_add_u32_e32 v2, v4, v2
	v_cmp_ne_u32_e32 vcc, v3, v2
	s_and_saveexec_b64 s[10:11], vcc
	s_xor_b64 s[10:11], exec, s[10:11]
	s_cbranch_execz .LBB0_2164
	buffer_inv sc1
	s_waitcnt lgkmcnt(0)
	v_mov_b32_e32 v0, 0x3000
	global_load_dword v0, v0, s[76:77] offset:1280 sc1
	s_add_u32 s14, s76, 0x3500
	s_addc_u32 s15, s77, 0
	s_waitcnt vmcnt(0)
	v_cmp_eq_u32_e32 vcc, v0, v1
	s_and_saveexec_b64 s[12:13], vcc
	s_cbranch_execz .LBB0_2163
	s_mov_b32 s3, 1
	s_mov_b64 s[16:17], 0
	v_mov_b32_e32 v0, 0
	s_branch .LBB0_2154

; __device__ __forceinline__ unsigned xb_ld(unsigned* p)              { return __hip_atomic_load(p, __ATOMIC_RELAXED, __HIP_MEMORY_SCOPE_AGENT); }
; __device__ __forceinline__ unsigned xb_add(unsigned* p, unsigned v) { return __hip_atomic_fetch_add(p, v, __ATOMIC_RELAXED, __HIP_MEMORY_SCOPE_AGENT); }
; #define XB_SPIN(cond, bar) do { unsigned _sp = 0; while (cond) { __builtin_amdgcn_s_sleep(1); \
;     if ((++_sp & 255u) == 0u) { if (xb_ld(&(bar)[XB_TMO])) break; if (_sp > XB_SPIN_CAP) { atomicAdd(&(bar)[XB_TMO], 1u); break; } } } } while (0)
; __device__ __forceinline__ void xcd_barrier(const XcdBarrier& b, bool leader) {
;     ...
;         if (nloc == 0u) { xcd_barrier_complete(bar, b.x, nloc, nx); b.st[0] = nloc; b.st[1] = nx; }
;         const unsigned old = xb_add(&bar[XB_XSUB(b.x)], 1u);
;         const unsigned gen = old / nloc;
;         if (old + 1u == (gen + 1u) * nloc) {
;             __builtin_amdgcn_fence(__ATOMIC_RELEASE, "agent");
;             asm volatile("s_waitcnt vmcnt(0)" ::: "memory");
;             const unsigned og = xb_add(&bar[XB_TOP], 1u);
;             const unsigned tg = og / nx;
;             if (og + 1u == (tg + 1u) * nx) xb_add(&bar[XB_TOPGEN], 1u);
;             else XB_SPIN(xb_ld(&bar[XB_TOPGEN]) == tg, bar);
;             __builtin_amdgcn_fence(__ATOMIC_ACQUIRE, "agent");
;             xb_add(&bar[XB_XGEN(b.x)], 1u);
;             asm volatile("s_waitcnt vmcnt(0)" ::: "memory");
;         } else {
;             XB_SPIN(xb_ld(&bar[XB_XGEN(b.x)]) == gen, bar);
.LBB0_2386:
	s_or_b64 exec, exec, s[10:11]
	v_cvt_f32_u32_e32 v4, v2
	s_waitcnt vmcnt(0)
	v_readfirstlane_b32 s6, v3
	v_sub_u32_e32 v3, 0, v2
	v_rcp_iflag_f32_e32 v4, v4
	v_add_u32_e32 v5, s6, v1
	v_mul_f32_e32 v4, 0x4f7ffffe, v4
	v_cvt_u32_f32_e32 v4, v4
	v_mul_lo_u32 v1, v3, v4
	v_mul_hi_u32 v1, v4, v1
	v_add_u32_e32 v1, v4, v1
	v_mul_hi_u32 v1, v5, v1
	v_mul_lo_u32 v3, v1, v2
	v_sub_u32_e32 v3, v5, v3
	v_add_u32_e32 v4, 1, v1
	v_cmp_ge_u32_e32 vcc, v3, v2
	s_nop 1
	v_cndmask_b32_e32 v1, v1, v4, vcc
	v_sub_u32_e32 v4, v3, v2
	v_cndmask_b32_e32 v3, v3, v4, vcc
	v_add_u32_e32 v4, 1, v1
	v_cmp_ge_u32_e32 vcc, v3, v2
	v_add_u32_e32 v3, 1, v5
	s_nop 0
	v_cndmask_b32_e32 v1, v1, v4, vcc
	v_mul_lo_u32 v4, v2, v1
	v_add_u32_e32 v2, v4, v2
	v_cmp_ne_u32_e32 vcc, v3, v2
	s_and_saveexec_b64 s[6:7], vcc
	s_xor_b64 s[6:7], exec, s[6:7]
	s_cbranch_execz .LBB0_2400
	buffer_inv sc1
	s_waitcnt lgkmcnt(0)
	v_mov_b32_e32 v0, 0x3000
	global_load_dword v0, v0, s[76:77] offset:1280 sc1
	s_add_u32 s12, s76, 0x3500
	s_addc_u32 s13, s77, 0
	s_waitcnt vmcnt(0)
	v_cmp_eq_u32_e32 vcc, v0, v1
	s_and_saveexec_b64 s[10:11], vcc
	s_cbranch_execz .LBB0_2399
	s_mov_b32 s24, 1
	s_mov_b64 s[14:15], 0
	v_mov_b32_e32 v0, 0
	s_branch .LBB0_2390
